# hgrn_scan: U/decay loads of 8 chunk steps issued together and double-buffered against the previous block's recurrence (was store + 2 loads + vmcnt(0) per step, 64 dependent round trips)
# speedup vs baseline: 1.0134x; 1.0134x over previous
; #define TIDX launder((int)threadIdx.x)
; DI float bf2f(bf16_t v) { return __uint_as_float(((unsigned)v) << 16); }
; DI bf16_t f2bf(float x) { return (bf16_t)(pk2(x, 0.f) & 0xffffu); }
; DI void hgrn_scan(const Params& p) {
;   const bf16_t* U = (const bf16_t*)(p.ws + E_U); const float* DL = (const float*)(p.ws + E_DL); bf16_t* ST = (bf16_t*)(p.ws + E_ST);
;   for (int idx = blockIdx.x * NTH + TIDX; idx < 16 * 128 * 128; idx += gridDim.x * NTH) {
;     const int k = idx & 127, v = (idx >> 7) & 127, bh = idx >> 14;
;     float S = 0.f;
; #pragma unroll 8
;     for (int c = 0; c < 64; ++c) {
;       const size_t o = (((size_t)bh * 64 + c) * 128 + v) * 128 + k;
;       ST[o] = f2bf(S);
;       S = DL[((size_t)bh * 64 + c) * 128 + k] * S + bf2f(U[o]);
;     }
;   }
.LBB0_291:
	s_nop 1
	s_add_u32 s6, s10, 0x351c5000
	s_addc_u32 s7, s11, 0
	s_add_u32 s8, s10, 0x31145000
	s_addc_u32 s9, s11, 0
	global_load_ushort v20, v6, s[8:9]
	global_load_dword v28, v10, s[6:7]
	s_add_u32 s8, s10, 0x3114d000
	s_addc_u32 s9, s11, 0
	global_load_ushort v21, v6, s[8:9]
	global_load_dword v29, v10, s[6:7] offset:512
	s_add_u32 s8, s10, 0x31155000
	s_addc_u32 s9, s11, 0
	global_load_ushort v22, v6, s[8:9]
	global_load_dword v30, v10, s[6:7] offset:1024
	s_add_u32 s8, s10, 0x3115d000
	s_addc_u32 s9, s11, 0
	global_load_ushort v23, v6, s[8:9]
	global_load_dword v31, v10, s[6:7] offset:1536
	s_add_u32 s8, s10, 0x31165000
	s_addc_u32 s9, s11, 0
	global_load_ushort v24, v6, s[8:9]
	global_load_dword v32, v10, s[6:7] offset:2048
	s_add_u32 s8, s10, 0x3116d000
	s_addc_u32 s9, s11, 0
	global_load_ushort v25, v6, s[8:9]
	global_load_dword v33, v10, s[6:7] offset:2560
	s_add_u32 s8, s10, 0x31175000
	s_addc_u32 s9, s11, 0
	global_load_ushort v26, v6, s[8:9]
	global_load_dword v34, v10, s[6:7] offset:3072
	s_add_u32 s8, s10, 0x3117d000
	s_addc_u32 s9, s11, 0
	global_load_ushort v27, v6, s[8:9]
	global_load_dword v35, v10, s[6:7] offset:3584
	v_mov_b32_e32 v12, v6
	v_add_u32_e32 v6, 0x40000, v6
	v_add_u32_e32 v10, 0x1000, v10
; #define TIDX launder((int)threadIdx.x)
; DI float bf2f(bf16_t v) { return __uint_as_float(((unsigned)v) << 16); }
; DI bf16_t f2bf(float x) { return (bf16_t)(pk2(x, 0.f) & 0xffffu); }
; DI void hgrn_scan(const Params& p) {
;     ...
;   for (int idx = blockIdx.x * NTH + TIDX; idx < 16 * 128 * 128; idx += gridDim.x * NTH) {
;     const int k = idx & 127, v = (idx >> 7) & 127, bh = idx >> 14;
;     float S = 0.f;
; #pragma unroll 8
;     for (int c = 0; c < 64; ++c) {
;       const size_t o = (((size_t)bh * 64 + c) * 128 + v) * 128 + k;
;       ST[o] = f2bf(S);
;       S = DL[((size_t)bh * 64 + c) * 128 + k] * S + bf2f(U[o]);
;     }
;   }
.Lscan_blk:
	s_add_u32 s6, s10, 0x351c5000
	s_addc_u32 s7, s11, 0
	s_add_u32 s8, s10, 0x31145000
	s_addc_u32 s9, s11, 0
	global_load_ushort v36, v6, s[8:9]
	global_load_dword v44, v10, s[6:7]
	s_add_u32 s8, s10, 0x3114d000
	s_addc_u32 s9, s11, 0
	global_load_ushort v37, v6, s[8:9]
	global_load_dword v45, v10, s[6:7] offset:512
	s_add_u32 s8, s10, 0x31155000
	s_addc_u32 s9, s11, 0
	global_load_ushort v38, v6, s[8:9]
	global_load_dword v46, v10, s[6:7] offset:1024
	s_add_u32 s8, s10, 0x3115d000
	s_addc_u32 s9, s11, 0
	global_load_ushort v39, v6, s[8:9]
	global_load_dword v47, v10, s[6:7] offset:1536
	s_add_u32 s8, s10, 0x31165000
	s_addc_u32 s9, s11, 0
	global_load_ushort v40, v6, s[8:9]
	global_load_dword v48, v10, s[6:7] offset:2048
	s_add_u32 s8, s10, 0x3116d000
	s_addc_u32 s9, s11, 0
	global_load_ushort v41, v6, s[8:9]
	global_load_dword v49, v10, s[6:7] offset:2560
	s_add_u32 s8, s10, 0x31175000
	s_addc_u32 s9, s11, 0
	global_load_ushort v42, v6, s[8:9]
	global_load_dword v50, v10, s[6:7] offset:3072
	s_add_u32 s8, s10, 0x3117d000
	s_addc_u32 s9, s11, 0
	global_load_ushort v43, v6, s[8:9]
	global_load_dword v51, v10, s[6:7] offset:3584
	v_cvt_pk_bf16_f32 v16, v5, s0
	s_add_u32 s8, s10, 0x29145000
	s_addc_u32 s9, s11, 0
	global_store_short v12, v16, s[8:9]
	s_waitcnt vmcnt(31)
	v_lshlrev_b32_e32 v18, 16, v20
	v_fmac_f32_e32 v18, v5, v28
	v_cvt_pk_bf16_f32 v16, v18, s0
	s_add_u32 s8, s10, 0x2914d000
	s_addc_u32 s9, s11, 0
	global_store_short v12, v16, s[8:9]
	s_waitcnt vmcnt(30)
	v_lshlrev_b32_e32 v19, 16, v21
	v_fmac_f32_e32 v19, v18, v29
	v_cvt_pk_bf16_f32 v16, v19, s0
	s_add_u32 s8, s10, 0x29155000
	s_addc_u32 s9, s11, 0
	global_store_short v12, v16, s[8:9]
	s_waitcnt vmcnt(29)
	v_lshlrev_b32_e32 v18, 16, v22
	v_fmac_f32_e32 v18, v19, v30
	v_cvt_pk_bf16_f32 v16, v18, s0
	s_add_u32 s8, s10, 0x2915d000
	s_addc_u32 s9, s11, 0
	global_store_short v12, v16, s[8:9]
	s_waitcnt vmcnt(28)
	v_lshlrev_b32_e32 v19, 16, v23
	v_fmac_f32_e32 v19, v18, v31
	v_cvt_pk_bf16_f32 v16, v19, s0
	s_add_u32 s8, s10, 0x29165000
	s_addc_u32 s9, s11, 0
	global_store_short v12, v16, s[8:9]
	s_waitcnt vmcnt(27)
	v_lshlrev_b32_e32 v18, 16, v24
	v_fmac_f32_e32 v18, v19, v32
	v_cvt_pk_bf16_f32 v16, v18, s0
	s_add_u32 s8, s10, 0x2916d000
	s_addc_u32 s9, s11, 0
	global_store_short v12, v16, s[8:9]
	s_waitcnt vmcnt(26)
	v_lshlrev_b32_e32 v19, 16, v25
	v_fmac_f32_e32 v19, v18, v33
	v_cvt_pk_bf16_f32 v16, v19, s0
	s_add_u32 s8, s10, 0x29175000
	s_addc_u32 s9, s11, 0
	global_store_short v12, v16, s[8:9]
	s_waitcnt vmcnt(25)
	v_lshlrev_b32_e32 v18, 16, v26
	v_fmac_f32_e32 v18, v19, v34
	v_cvt_pk_bf16_f32 v16, v18, s0
	s_add_u32 s8, s10, 0x2917d000
	s_addc_u32 s9, s11, 0
	global_store_short v12, v16, s[8:9]
	s_waitcnt vmcnt(24)
	v_lshlrev_b32_e32 v5, 16, v27
	v_fmac_f32_e32 v5, v18, v35
	v_mov_b32_e32 v12, v6
	v_add_u32_e32 v6, 0x40000, v6
	v_add_u32_e32 v10, 0x1000, v10
	s_add_u32 s6, s10, 0x351c5000
	s_addc_u32 s7, s11, 0
	s_add_u32 s8, s10, 0x31145000
	s_addc_u32 s9, s11, 0
	global_load_ushort v20, v6, s[8:9]
	global_load_dword v28, v10, s[6:7]
	s_add_u32 s8, s10, 0x3114d000
	s_addc_u32 s9, s11, 0
	global_load_ushort v21, v6, s[8:9]
	global_load_dword v29, v10, s[6:7] offset:512
	s_add_u32 s8, s10, 0x31155000
	s_addc_u32 s9, s11, 0
	global_load_ushort v22, v6, s[8:9]
	global_load_dword v30, v10, s[6:7] offset:1024
	s_add_u32 s8, s10, 0x3115d000
	s_addc_u32 s9, s11, 0
	global_load_ushort v23, v6, s[8:9]
	global_load_dword v31, v10, s[6:7] offset:1536
	s_add_u32 s8, s10, 0x31165000
	s_addc_u32 s9, s11, 0
	global_load_ushort v24, v6, s[8:9]
	global_load_dword v32, v10, s[6:7] offset:2048
	s_add_u32 s8, s10, 0x3116d000
	s_addc_u32 s9, s11, 0
	global_load_ushort v25, v6, s[8:9]
	global_load_dword v33, v10, s[6:7] offset:2560
	s_add_u32 s8, s10, 0x31175000
	s_addc_u32 s9, s11, 0
	global_load_ushort v26, v6, s[8:9]
	global_load_dword v34, v10, s[6:7] offset:3072
	s_add_u32 s8, s10, 0x3117d000
	s_addc_u32 s9, s11, 0
	global_load_ushort v27, v6, s[8:9]
	global_load_dword v35, v10, s[6:7] offset:3584
	v_cvt_pk_bf16_f32 v16, v5, s0
	s_add_u32 s8, s10, 0x29145000
	s_addc_u32 s9, s11, 0
	global_store_short v12, v16, s[8:9]
	s_waitcnt vmcnt(39)
	v_lshlrev_b32_e32 v18, 16, v36
	v_fmac_f32_e32 v18, v5, v44
	v_cvt_pk_bf16_f32 v16, v18, s0
	s_add_u32 s8, s10, 0x2914d000
	s_addc_u32 s9, s11, 0
	global_store_short v12, v16, s[8:9]
	s_waitcnt vmcnt(38)
	v_lshlrev_b32_e32 v19, 16, v37
	v_fmac_f32_e32 v19, v18, v45
	v_cvt_pk_bf16_f32 v16, v19, s0
	s_add_u32 s8, s10, 0x29155000
	s_addc_u32 s9, s11, 0
	global_store_short v12, v16, s[8:9]
	s_waitcnt vmcnt(37)
	v_lshlrev_b32_e32 v18, 16, v38
	v_fmac_f32_e32 v18, v19, v46
	v_cvt_pk_bf16_f32 v16, v18, s0
	s_add_u32 s8, s10, 0x2915d000
	s_addc_u32 s9, s11, 0
	global_store_short v12, v16, s[8:9]
	s_waitcnt vmcnt(36)
	v_lshlrev_b32_e32 v19, 16, v39
	v_fmac_f32_e32 v19, v18, v47
	v_cvt_pk_bf16_f32 v16, v19, s0
	s_add_u32 s8, s10, 0x29165000
	s_addc_u32 s9, s11, 0
	global_store_short v12, v16, s[8:9]
	s_waitcnt vmcnt(35)
	v_lshlrev_b32_e32 v18, 16, v40
	v_fmac_f32_e32 v18, v19, v48
	v_cvt_pk_bf16_f32 v16, v18, s0
	s_add_u32 s8, s10, 0x2916d000
	s_addc_u32 s9, s11, 0
	global_store_short v12, v16, s[8:9]
	s_waitcnt vmcnt(34)
	v_lshlrev_b32_e32 v19, 16, v41
	v_fmac_f32_e32 v19, v18, v49
	v_cvt_pk_bf16_f32 v16, v19, s0
	s_add_u32 s8, s10, 0x29175000
	s_addc_u32 s9, s11, 0
	global_store_short v12, v16, s[8:9]
	s_waitcnt vmcnt(33)
	v_lshlrev_b32_e32 v18, 16, v42
	v_fmac_f32_e32 v18, v19, v50
	v_cvt_pk_bf16_f32 v16, v18, s0
	s_add_u32 s8, s10, 0x2917d000
	s_addc_u32 s9, s11, 0
	global_store_short v12, v16, s[8:9]
	s_waitcnt vmcnt(32)
	v_lshlrev_b32_e32 v5, 16, v43
	v_fmac_f32_e32 v5, v18, v51
	v_mov_b32_e32 v12, v6
	v_add_u32_e32 v6, 0x40000, v6
	v_add_u32_e32 v10, 0x1000, v10
	s_add_i32 s4, s4, -16
	s_cmp_eq_u32 s4, 0
	s_cbranch_scc0 .Lscan_blk
	s_waitcnt vmcnt(0)
	v_readlane_b32 s4, v250, 10
	s_nop 1
	v_add_u32_e32 v3, s4, v3
	s_mov_b32 s4, 0x3ffff
	v_cmp_lt_i32_e32 vcc, s4, v3
	s_or_b64 s[2:3], vcc, s[2:3]
	s_andn2_b64 exec, exec, s[2:3]
	s_cbranch_execnz .LBB0_290
